# stick-breaking inner loop: log(1+e) via one fma, exp clamp instead of min, 2x unroll with two register sets so the prefetched tile is not copied
# speedup vs baseline: 1.0120x; 1.0037x over previous
; __device__ __forceinline__ int otid() { int t = threadIdx.x; asm volatile("" : "+v"(t)); return t; }
; __device__ __forceinline__ void sb_load(SbFrags& F, const bf16_t* Pm, const bf16_t* VT, size_t tok0, int kv0, int h, int r32, int hi) {
;     const bf16_t* krow = Pm + (tok0 + kv0 + r32) * PW + PC_SBK + h * 64;
; #pragma unroll
;     for (int s = 0; s < 4; ++s) F.kf[s] = *(const bf16x8*)(krow + 16 * s + 8 * hi);
; #pragma unroll
;     for (int s = 0; s < 2; ++s) {
;         const bf16_t* v0p = VT + (size_t)(h * 64 + r32) * VTLD + tok0 + kv0 + 16 * s + 4 * hi; const bf16_t* v1p = v0p + (size_t)32 * VTLD;
;         F.v[4 * s + 0] = *(const s16x4*)v0p; F.v[4 * s + 1] = *(const s16x4*)(v0p + 8); F.v[4 * s + 2] = *(const s16x4*)v1p; F.v[4 * s + 3] = *(const s16x4*)(v1p + 8);
;     }
; }
; template <bool DRY> __device__ __forceinline__ void sb_unit(int b, int h, int qi, bf16_t* Pm, const bf16_t* VT) {
;     const int lane = otid() & 63, r32 = lane & 31, hi = lane >> 5;
;     const size_t tok0 = (size_t)b * SEQ; const int q0 = qi * 32;
;     bf16_t* qrow = Pm + (tok0 + q0 + r32) * PW + PC_SBQ + h * 64;
;     bf16x8 qf[4];
; #pragma unroll
;     for (int s = 0; s < 4; ++s) qf[s] = *(const bf16x8*)(qrow + 16 * s + 8 * hi);
;     float R = 0.f; f32x16 o0 = {}, o1 = {};
;     SbFrags cur, nxt;
;     sb_load(cur, Pm, VT, tok0, qi * 32, h, r32, hi);
; #pragma unroll 1
;     ...
;         sb_load(nxt, Pm, VT, tok0, (kt > 0 ? kt - 1 : 0) * 32, h, r32, hi);
;         f32x16 p = {};
; #pragma unroll
;         for (int s = 0; s < 4; ++s) p = __builtin_amdgcn_mfma_f32_32x32x16_bf16(cur.kf[s], qf[s], p, 0, 0, 0);
;         const bool diag = (kt == qi);
.LBB0_741:
	v_ashrrev_i32_e32 v4, 9, v3
	v_mov_b32_e32 v0, v234
	s_waitcnt vmcnt(0)
	v_and_b32_e32 v100, 63, v3
	v_ashrrev_i32_e32 v5, 31, v4
	v_and_b32_e32 v15, 31, v0
	v_bfe_u32 v16, v0, 5, 1
	v_lshlrev_b64 v[0:1], 11, v[4:5]
	v_lshlrev_b32_e32 v17, 5, v100
	v_or3_b32 v8, v15, v17, v0
	v_mov_b64_e32 v[6:7], s[42:43]
	v_and_b32_e32 v14, 0x1c0, v3
	v_mad_u64_u32 v[6:7], s[4:5], v8, s24, v[6:7]
	v_mad_i32_i24 v7, v1, s24, v7
	v_lshlrev_b32_e32 v8, 1, v14
	v_mov_b32_e32 v9, v2
	v_lshl_add_u64 v[84:85], v[6:7], 0, v[8:9]
	v_lshlrev_b32_e32 v10, 4, v16
	v_mov_b32_e32 v11, v2
	v_lshl_add_u64 v[12:13], v[84:85], 0, v[10:11]
	global_load_dwordx4 v[52:55], v[12:13], off offset:1280
	global_load_dwordx4 v[56:59], v[12:13], off offset:1312
	global_load_dwordx4 v[60:63], v[12:13], off offset:1344
	global_load_dwordx4 v[64:67], v[12:13], off offset:1376
	v_or_b32_e32 v12, v15, v14
	v_mul_u32_u24_e32 v12, 0x8200, v12
	v_lshlrev_b32_e32 v12, 1, v12
	v_mov_b32_e32 v13, v2
	v_lshl_add_u64 v[12:13], s[38:39], 0, v[12:13]
	v_lshlrev_b64 v[4:5], 12, v[4:5]
	v_lshlrev_b32_e32 v6, 4, v16
	v_mov_b32_e32 v7, v2
	v_lshl_add_u64 v[4:5], v[12:13], 0, v[4:5]
	v_lshlrev_b32_e32 v12, 6, v100
	v_mov_b32_e32 v13, v2
	v_lshl_add_u64 v[12:13], v[4:5], 0, v[12:13]
	v_lshl_add_u64 v[88:89], v[4:5], 0, v[6:7]
	v_xor_b32_e32 v4, 32, v238
	v_add_u32_e32 v5, 64, v239
	v_cmp_lt_i32_e32 vcc, v4, v5
	v_lshlrev_b32_e32 v86, 2, v16
	v_and_b32_e32 v98, 63, v87
	v_cndmask_b32_e32 v4, v238, v4, vcc
	v_lshlrev_b32_e32 v101, 2, v4
	v_or_b32_e32 v4, 1, v86
	v_cmp_lt_u32_e64 s[46:47], v4, v15
	v_or_b32_e32 v4, 2, v86
	v_cmp_lt_u32_e64 s[48:49], v4, v15
	v_or_b32_e32 v4, 3, v86
	v_cmp_lt_u32_e64 s[50:51], v4, v15
	v_or_b32_e32 v4, 8, v86
	v_cmp_lt_u32_e64 s[52:53], v4, v15
	v_or_b32_e32 v4, 9, v86
	v_cmp_lt_u32_e64 s[54:55], v4, v15
	v_or_b32_e32 v4, 10, v86
	v_cmp_lt_u32_e64 s[56:57], v4, v15
	v_or_b32_e32 v4, 11, v86
	v_cmp_lt_u32_e64 s[58:59], v4, v15
	v_or_b32_e32 v4, 16, v86
	v_cmp_lt_u32_e64 s[60:61], v4, v15
	v_or_b32_e32 v4, 17, v86
	v_cmp_lt_u32_e64 s[62:63], v4, v15
	v_or_b32_e32 v4, 18, v86
	v_cmp_lt_u32_e64 s[64:65], v4, v15
	v_or_b32_e32 v4, 19, v86
	v_cmp_lt_u32_e64 s[66:67], v4, v15
	v_or_b32_e32 v4, 24, v86
	v_cmp_lt_u32_e64 s[68:69], v4, v15
	v_or_b32_e32 v4, 25, v86
	v_cmp_lt_u32_e64 s[70:71], v4, v15
	v_or_b32_e32 v4, 26, v86
	v_cmp_lt_u32_e64 s[72:73], v4, v15
	v_or_b32_e32 v4, 27, v86
	v_or_b32_e32 v0, v0, v15
	v_cmp_lt_u32_e64 s[74:75], v4, v15
	v_lshl_add_u64 v[4:5], s[42:43], 0, v[8:9]
	v_mov_b32_e32 v102, 0
	v_lshlrev_b32_e32 v99, 5, v98
	v_or_b32_e32 v90, v0, v17
	v_mov_b32_e32 v91, v1
	v_lshl_add_u64 v[94:95], v[12:13], 0, v[6:7]
	s_mov_b32 s28, 0
	v_cmp_eq_u32_e64 s[12:13], 0, v16
	v_cmp_lt_u32_e64 s[44:45], v86, v15
	v_lshl_add_u64 v[92:93], v[4:5], 0, v[10:11]
	s_mov_b64 s[34:35], 0
	v_mov_b32_e32 v4, 0
	v_mov_b32_e32 v5, v102
	v_mov_b32_e32 v6, v102
	v_mov_b32_e32 v7, v102
	v_mov_b32_e32 v8, v102
	v_mov_b32_e32 v9, v102
	v_mov_b32_e32 v10, v102
	v_mov_b32_e32 v11, v102
	v_mov_b32_e32 v12, v102
	v_mov_b32_e32 v13, v102
	v_mov_b32_e32 v14, v102
	v_mov_b32_e32 v15, v102
	v_mov_b32_e32 v16, v102
	v_mov_b32_e32 v17, v102
	v_mov_b32_e32 v18, v102
	v_mov_b32_e32 v19, v102
	v_mov_b32_e32 v20, 0
	v_mov_b32_e32 v21, v102
	v_mov_b32_e32 v22, v102
	v_mov_b32_e32 v23, v102
	v_mov_b32_e32 v24, v102
	v_mov_b32_e32 v25, v102
	v_mov_b32_e32 v26, v102
	v_mov_b32_e32 v27, v102
	v_mov_b32_e32 v28, v102
	v_mov_b32_e32 v29, v102
	v_mov_b32_e32 v30, v102
	v_mov_b32_e32 v31, v102
	v_mov_b32_e32 v32, v102
	v_mov_b32_e32 v33, v102
	v_mov_b32_e32 v34, v102
	v_mov_b32_e32 v35, v102
	v_med3_i32 v36, v100, 0, 1
	v_lshlrev_b32_e32 v36, 5, v36
	s_mov_b32 s4, 0x208000
	v_sub_u32_e32 v40, v99, v36
	v_add_co_u32_e32 v36, vcc, s4, v94
	v_mov_b32_e32 v41, v2
	s_nop 0
	v_addc_co_u32_e32 v37, vcc, 0, v95, vcc
	global_load_dwordx4 v[68:71], v[36:37], off offset:32
	global_load_dwordx4 v[72:75], v[94:95], off offset:32
	global_load_dwordx4 v[76:79], v[36:37], off
	global_load_dwordx4 v[80:83], v[94:95], off
	v_mad_u64_u32 v[36:37], s[4:5], v90, s24, v[92:93]
	v_mov_b32_e32 v38, v37
	v_mad_u64_u32 v[38:39], s[4:5], v91, s24, v[38:39]
	v_mov_b32_e32 v37, v38
	global_load_dwordx4 v[184:187], v[36:37], off offset:2400
	global_load_dwordx4 v[180:183], v[36:37], off offset:2368
	global_load_dwordx4 v[176:179], v[36:37], off offset:2336
	s_nop 0
	global_load_dwordx4 v[172:175], v[36:37], off offset:2304
	v_lshl_add_u64 v[90:91], v[0:1], 0, v[40:41]
	v_lshl_add_u64 v[94:95], v[40:41], 1, v[88:89]
	v_add_u32_e32 v100, -1, v100
	v_subrev_u32_e32 v99, 32, v99
; __device__ __forceinline__ int crow(int r, int hi) { return (r & 3) + 8 * (r >> 2) + 4 * hi; }
; __device__ __forceinline__ void sb_load(SbFrags& F, const bf16_t* Pm, const bf16_t* VT, size_t tok0, int kv0, int h, int r32, int hi) {
;     const bf16_t* krow = Pm + (tok0 + kv0 + r32) * PW + PC_SBK + h * 64;
; #pragma unroll
;     for (int s = 0; s < 4; ++s) F.kf[s] = *(const bf16x8*)(krow + 16 * s + 8 * hi);
; #pragma unroll
;     for (int s = 0; s < 2; ++s) {
;         const bf16_t* v0p = VT + (size_t)(h * 64 + r32) * VTLD + tok0 + kv0 + 16 * s + 4 * hi; const bf16_t* v1p = v0p + (size_t)32 * VTLD;
;         F.v[4 * s + 0] = *(const s16x4*)v0p; F.v[4 * s + 1] = *(const s16x4*)(v0p + 8); F.v[4 * s + 2] = *(const s16x4*)v1p; F.v[4 * s + 3] = *(const s16x4*)(v1p + 8);
;     }
; }
; template <bool DRY> __device__ __forceinline__ void sb_unit(int b, int h, int qi, bf16_t* Pm, const bf16_t* VT) {
;     ...
;         sb_load(nxt, Pm, VT, tok0, (kt > 0 ? kt - 1 : 0) * 32, h, r32, hi);
;         f32x16 p = {};
; #pragma unroll
;         for (int s = 0; s < 4; ++s) p = __builtin_amdgcn_mfma_f32_32x32x16_bf16(cur.kf[s], qf[s], p, 0, 0, 0);
;         const bool diag = (kt == qi);
;         float lk[16], inner[16], Tg[4], TP[4], pre[4];
; #pragma unroll
;         for (int r = 0; r < 16; ++r) {
;             const float z = p[r] * 0.125f; p[r] = z;
;             const float e = __expf(-fabsf(z)); const float sp = fmaxf(z, 0.f) + __logf(1.f + e);
;             const bool valid = !diag || (crow(r, hi) < r32);
;             lk[r] = valid ? -sp : 0.f;
.LBB0_742:
	v_med3_i32 v36, v100, 0, 1
	v_lshlrev_b32_e32 v36, 5, v36
	s_mov_b32 s4, 0x208000
	v_sub_u32_e32 v40, v99, v36
	v_add_co_u32_e32 v36, vcc, s4, v94
	v_mov_b32_e32 v41, v2
	s_nop 0
	v_addc_co_u32_e32 v37, vcc, 0, v95, vcc
	global_load_dwordx4 v[156:159], v[36:37], off offset:32
	global_load_dwordx4 v[160:163], v[94:95], off offset:32
	global_load_dwordx4 v[164:167], v[36:37], off
	global_load_dwordx4 v[168:171], v[94:95], off
	v_mad_u64_u32 v[36:37], s[4:5], v90, s24, v[92:93]
	v_mov_b32_e32 v38, v37
	v_mad_u64_u32 v[38:39], s[4:5], v91, s24, v[38:39]
	v_mov_b32_e32 v37, v38
	global_load_dwordx4 v[152:155], v[36:37], off offset:2400
	global_load_dwordx4 v[148:151], v[36:37], off offset:2368
	global_load_dwordx4 v[144:147], v[36:37], off offset:2336
	s_nop 0
	global_load_dwordx4 v[140:143], v[36:37], off offset:2304
	v_lshl_add_u64 v[90:91], v[0:1], 0, v[40:41]
	v_lshl_add_u64 v[94:95], v[40:41], 1, v[88:89]
	s_cmp_lg_u32 s28, 0
	s_cselect_b64 s[22:23], -1, 0
	s_or_b64 s[76:77], s[44:45], s[22:23]
	s_or_b64 s[78:79], s[46:47], s[22:23]
	s_or_b64 s[80:81], s[48:49], s[22:23]
	s_or_b64 s[88:89], s[56:57], s[22:23]
	s_or_b64 s[94:95], s[62:63], s[22:23]
	s_or_b64 s[96:97], s[64:65], s[22:23]
	s_or_b64 s[84:85], s[52:53], s[22:23]
	s_or_b64 s[86:87], s[54:55], s[22:23]
	s_or_b64 s[92:93], s[60:61], s[22:23]
	s_or_b64 s[90:91], s[58:59], s[22:23]
	s_or_b64 s[82:83], s[50:51], s[22:23]
	v_add_u32_e32 v100, -1, v100
	v_subrev_u32_e32 v99, 32, v99
	s_waitcnt vmcnt(8)
	v_mfma_f32_32x32x16_bf16 v[36:51], v[172:175], v[52:55], 0
	v_mfma_f32_32x32x16_bf16 v[36:51], v[176:179], v[56:59], v[36:51]
	v_mfma_f32_32x32x16_bf16 v[36:51], v[180:183], v[60:63], v[36:51]
	v_mfma_f32_32x32x16_bf16 v[36:51], v[184:187], v[64:67], v[36:51]
	v_permlane32_swap_b32_e32 v80, v82
	v_permlane32_swap_b32_e32 v81, v83
	v_permlane32_swap_b32_e32 v72, v74
	v_permlane32_swap_b32_e32 v73, v75
	v_permlane32_swap_b32_e32 v76, v78
	v_permlane32_swap_b32_e32 v77, v79
	v_permlane32_swap_b32_e32 v68, v70
	v_permlane32_swap_b32_e32 v69, v71
	s_nop 3
	v_mul_f32_e32 v96, 0x3e000000, v36
	v_mul_f32_e64 v97, |v96|, s25
	v_exp_f32_e32 v97, v97
	v_max_f32_e32 v96, 0, v96
	v_add_f32_e32 v97, 1.0, v97
	v_log_f32_e32 v97, v97
	s_nop 0
	v_fmamk_f32 v96, v97, 0x3f317217, v96
	v_cndmask_b32_e64 v103, 0, -v96, s[76:77]
	v_mul_f32_e32 v96, 0x3e000000, v37
	v_mul_f32_e64 v97, |v96|, s25
	v_exp_f32_e32 v97, v97
	v_max_f32_e32 v96, 0, v96
	v_fmamk_f32 v36, v36, 0x3e000000, v103
	v_add_f32_e32 v97, 1.0, v97
	v_log_f32_e32 v97, v97
	s_nop 0
	v_fmamk_f32 v96, v97, 0x3f317217, v96
	v_cndmask_b32_e64 v108, 0, -v96, s[78:79]
	v_mul_f32_e32 v96, 0x3e000000, v38
	v_mul_f32_e64 v97, |v96|, s25
	v_exp_f32_e32 v97, v97
	v_max_f32_e32 v96, 0, v96
	v_add_f32_e32 v97, 1.0, v97
	v_log_f32_e32 v97, v97
	s_nop 0
	v_fmamk_f32 v96, v97, 0x3f317217, v96
	v_cndmask_b32_e64 v109, 0, -v96, s[80:81]
	v_mul_f32_e32 v96, 0x3e000000, v39
	v_mul_f32_e64 v39, |v96|, s25
	v_exp_f32_e32 v39, v39
	v_max_f32_e32 v97, 0, v96
	v_add_f32_e32 v39, 1.0, v39
	v_log_f32_e32 v39, v39
	s_nop 0
	v_fmamk_f32 v110, v39, 0x3f317217, v97
	v_mul_f32_e32 v39, 0x3e000000, v40
	v_mul_f32_e64 v97, |v39|, s25
	v_exp_f32_e32 v97, v97
	v_max_f32_e32 v39, 0, v39
	v_add_f32_e32 v97, 1.0, v97
	v_log_f32_e32 v97, v97
	s_nop 0
	v_fmamk_f32 v39, v97, 0x3f317217, v39
	v_mul_f32_e32 v97, 0x3e000000, v41
	v_mul_f32_e64 v104, |v97|, s25
	v_exp_f32_e32 v104, v104
	v_max_f32_e32 v97, 0, v97
	v_cndmask_b32_e64 v39, 0, -v39, s[84:85]
	v_add_f32_e32 v104, 1.0, v104
	v_log_f32_e32 v104, v104
	s_nop 0
	v_fmamk_f32 v97, v104, 0x3f317217, v97
	v_mul_f32_e32 v104, 0x3e000000, v42
	v_mul_f32_e64 v105, |v104|, s25
	v_exp_f32_e32 v105, v105
	v_max_f32_e32 v104, 0, v104
	v_cndmask_b32_e64 v97, 0, -v97, s[86:87]
	v_add_f32_e32 v105, 1.0, v105
	v_log_f32_e32 v105, v105
	s_nop 0
	v_fmamk_f32 v104, v105, 0x3f317217, v104
	v_cndmask_b32_e64 v111, 0, -v104, s[88:89]
	v_mul_f32_e32 v104, 0x3e000000, v43
	v_mul_f32_e64 v43, |v104|, s25
	v_exp_f32_e32 v43, v43
	v_max_f32_e32 v105, 0, v104
	v_add_f32_e32 v43, 1.0, v43
	v_log_f32_e32 v43, v43
	s_nop 0
	v_fmamk_f32 v43, v43, 0x3f317217, v105
	v_mul_f32_e32 v105, 0x3e000000, v44
	v_mul_f32_e64 v106, |v105|, s25
	v_exp_f32_e32 v106, v106
	v_max_f32_e32 v105, 0, v105
	v_add_f32_e32 v106, 1.0, v106
	v_log_f32_e32 v106, v106
	s_nop 0
	v_fmamk_f32 v105, v106, 0x3f317217, v105
	v_mul_f32_e32 v106, 0x3e000000, v45
	v_mul_f32_e64 v107, |v106|, s25
	v_exp_f32_e32 v107, v107
	v_max_f32_e32 v106, 0, v106
	v_cndmask_b32_e64 v105, 0, -v105, s[92:93]
	v_add_f32_e32 v107, 1.0, v107
	v_log_f32_e32 v107, v107
	s_nop 0
	v_fmamk_f32 v106, v107, 0x3f317217, v106
	v_cndmask_b32_e64 v112, 0, -v106, s[94:95]
	v_mul_f32_e32 v106, 0x3e000000, v46
	v_mul_f32_e64 v107, |v106|, s25
	v_exp_f32_e32 v107, v107
	v_max_f32_e32 v106, 0, v106
	v_add_f32_e32 v107, 1.0, v107
	v_log_f32_e32 v107, v107
	s_nop 0
	v_fmamk_f32 v106, v107, 0x3f317217, v106
	v_cndmask_b32_e64 v113, 0, -v106, s[96:97]
	v_mul_f32_e32 v106, 0x3e000000, v47
	v_mul_f32_e64 v47, |v106|, s25
	v_exp_f32_e32 v47, v47
	v_max_f32_e32 v107, 0, v106
	v_add_f32_e32 v47, 1.0, v47
	v_log_f32_e32 v47, v47
	s_nop 0
	v_fmamk_f32 v47, v47, 0x3f317217, v107
	v_mul_f32_e32 v107, 0x3e000000, v48
	v_mul_f32_e64 v114, |v107|, s25
	v_exp_f32_e32 v114, v114
	v_max_f32_e32 v107, 0, v107
	s_or_b64 s[4:5], s[66:67], s[22:23]
	v_add_f32_e32 v114, 1.0, v114
	v_log_f32_e32 v114, v114
	s_nop 0
	v_fmamk_f32 v107, v114, 0x3f317217, v107
	s_or_b64 s[6:7], s[68:69], s[22:23]
	v_cndmask_b32_e64 v114, 0, -v107, s[6:7]
	v_mul_f32_e32 v107, 0x3e000000, v49
	v_mul_f32_e64 v115, |v107|, s25
	v_exp_f32_e32 v115, v115
	v_max_f32_e32 v107, 0, v107
	v_add_f32_e32 v115, 1.0, v115
	v_log_f32_e32 v115, v115
	s_nop 0
	v_fmamk_f32 v107, v115, 0x3f317217, v107
	s_or_b64 s[8:9], s[70:71], s[22:23]
	v_cndmask_b32_e64 v115, 0, -v107, s[8:9]
	v_mul_f32_e32 v107, 0x3e000000, v50
	v_mul_f32_e64 v116, |v107|, s25
	v_exp_f32_e32 v116, v116
	v_max_f32_e32 v107, 0, v107
	v_add_f32_e32 v116, 1.0, v116
	v_log_f32_e32 v116, v116
	s_nop 0
	v_fmamk_f32 v107, v116, 0x3f317217, v107
	s_or_b64 s[10:11], s[72:73], s[22:23]
	v_cndmask_b32_e64 v116, 0, -v107, s[10:11]
	v_mul_f32_e32 v107, 0x3e000000, v51
	v_mul_f32_e64 v117, |v107|, s25
	v_exp_f32_e32 v117, v117
	v_max_f32_e32 v107, 0, v107
	v_add_f32_e32 v117, 1.0, v117
	v_log_f32_e32 v117, v117
	s_nop 0
	v_fmamk_f32 v107, v117, 0x3f317217, v107
	s_or_b64 vcc, s[74:75], s[22:23]
	v_cndmask_b32_e64 v117, 0, -v107, vcc
	v_add_f32_e32 v118, v117, v116
	v_add_f32_e32 v119, v115, v118
	v_add_f32_e32 v107, v114, v119
	ds_bpermute_b32 v120, v101, v107
	v_fmac_f32_e32 v114, 0x3e000000, v48
	v_fmac_f32_e32 v115, 0x3e000000, v49
	v_fmac_f32_e32 v116, 0x3e000000, v50
	s_waitcnt lgkmcnt(0)
; __device__ __forceinline__ unsigned cvtpk(float lo, float hi) { f32x2_t v = {lo, hi}; bf16x2_t b = __builtin_convertvector(v, bf16x2_t); return __builtin_bit_cast(unsigned, b); }
; __device__ __forceinline__ int crow(int r, int hi) { return (r & 3) + 8 * (r >> 2) + 4 * hi; }
; template <bool DRY> __device__ __forceinline__ void sb_unit(int b, int h, int qi, bf16_t* Pm, const bf16_t* VT) {
;     ...
;         }
; #pragma unroll
;         for (int g = 0; g < 4; ++g) {
;             const float s3 = lk[4 * g + 3], s2 = s3 + lk[4 * g + 2], s1 = s2 + lk[4 * g + 1];
;             inner[4 * g + 3] = 0.f; inner[4 * g + 2] = s3; inner[4 * g + 1] = s2; inner[4 * g] = s1; Tg[g] = s1 + lk[4 * g];
;             TP[g] = __shfl_xor(Tg[g], 32);
;         }
;         float run = 0.f;
; #pragma unroll
;         for (int g = 3; g >= 0; --g) { pre[g] = run + (hi == 0 ? TP[g] : 0.f); run += Tg[g] + TP[g]; }
; #pragma unroll
;         for (int r = 0; r < 16; ++r) {
;             const bool valid = !diag || (crow(r, hi) < r32);
;             const float ex = fminf(p[r] + lk[r] + R + pre[r >> 2] + inner[r], 0.f);
;             p[r] = valid ? __expf(ex) : 0.f;
;         }
;         R += run;
; #pragma unroll
;         for (int s = 0; s < 2; ++s) {
;             const u32x4 pw = (u32x4){cvtpk(p[8 * s + 0], p[8 * s + 1]), cvtpk(p[8 * s + 2], p[8 * s + 3]), cvtpk(p[8 * s + 4], p[8 * s + 5]), cvtpk(p[8 * s + 6], p[8 * s + 7])};
;             const bf16x8 pf = __builtin_bit_cast(bf16x8, pw);
;             const s16x4 l0 = cur.v[4 * s], h0 = cur.v[4 * s + 1], l1 = cur.v[4 * s + 2], h1 = cur.v[4 * s + 3];
;             const bf16x8 v0 = (bf16x8){l0[0], l0[1], l0[2], l0[3], h0[0], h0[1], h0[2], h0[3]};
;             const bf16x8 v1 = (bf16x8){l1[0], l1[1], l1[2], l1[3], h1[0], h1[1], h1[2], h1[3]};
;             o0 = __builtin_amdgcn_mfma_f32_32x32x16_bf16(v0, pf, o0, 0, 0, 0);
;             o1 = __builtin_amdgcn_mfma_f32_32x32x16_bf16(v1, pf, o1, 0, 0, 0);
;         }
;         if (__all(R < -104.f)) break;
	v_add_f32_e32 v121, 0, v120
	v_add_f32_e32 v107, v107, v120
	v_add_f32_e32 v120, v102, v36
	v_fmamk_f32 v36, v37, 0x3e000000, v108
	v_add_f32_e32 v122, v102, v36
	v_fmamk_f32 v36, v38, 0x3e000000, v109
	v_add_f32_e32 v123, v102, v36
	v_fmamk_f32 v36, v40, 0x3e000000, v39
	v_add_f32_e32 v124, v102, v36
	v_fmamk_f32 v36, v41, 0x3e000000, v97
	v_add_f32_e32 v125, v102, v36
	v_fmamk_f32 v36, v42, 0x3e000000, v111
	v_add_f32_e32 v126, v102, v36
	v_fmamk_f32 v36, v44, 0x3e000000, v105
	v_add_f32_e32 v127, v102, v36
	v_fmamk_f32 v36, v45, 0x3e000000, v112
	v_add_f32_e32 v128, v102, v36
	v_fmamk_f32 v36, v46, 0x3e000000, v113
	v_add_f32_e32 v46, v102, v36
	v_cndmask_b32_e64 v36, 0, -v47, s[4:5]
	v_add_f32_e32 v47, v36, v113
	v_add_f32_e32 v112, v112, v47
	v_add_f32_e32 v38, v105, v112
	ds_bpermute_b32 v40, v101, v38
	v_add_f32_e32 v107, 0, v107
	v_cndmask_b32_e64 v121, 0, v121, s[12:13]
	s_waitcnt lgkmcnt(0)
	v_add_f32_e32 v38, v38, v40
	v_add_f32_e32 v105, v38, v107
	v_cndmask_b32_e64 v38, 0, -v43, s[90:91]
	v_add_f32_e32 v111, v38, v111
	v_add_f32_e32 v113, v97, v111
	v_cndmask_b32_e64 v37, 0, v40, s[12:13]
	v_add_f32_e32 v40, v39, v113
	ds_bpermute_b32 v41, v101, v40
	s_waitcnt lgkmcnt(0)
	v_cndmask_b32_e64 v39, 0, v41, s[12:13]
	v_add_f32_e32 v42, v40, v41
	v_pk_add_f32 v[40:41], v[104:105], v[38:39]
	v_add_f32_e32 v97, v42, v105
	v_cndmask_b32_e64 v42, 0, -v110, s[82:83]
	v_add_f32_e32 v39, v102, v40
	v_add_f32_e32 v40, v42, v109
	v_add_f32_e32 v104, v108, v40
	v_add_f32_e32 v44, v103, v104
	ds_bpermute_b32 v45, v101, v44
	s_waitcnt lgkmcnt(0)
	v_cndmask_b32_e64 v43, 0, v45, s[12:13]
	v_add_f32_e32 v103, v44, v45
	v_pk_add_f32 v[44:45], v[96:97], v[42:43]
	v_add_f32_e32 v97, v103, v97
	v_add_f32_e32 v43, v102, v44
	v_add_f32_e32 v44, v120, v45
	v_add_f32_e32 v44, v104, v44
	v_add_f32_e32 v104, v126, v41
	v_add_f32_e32 v38, v38, v104
	v_mul_f32_e32 v38, 0x3fb8aa3b, v38
	v_exp_f32_e64 v38, v38 clamp
	v_add_f32_e32 v96, v122, v45
	v_add_f32_e32 v40, v40, v96
	v_add_f32_e32 v96, v123, v45
	v_cndmask_b32_e64 v104, 0, v38, s[88:89]
	v_add_f32_e32 v38, v39, v41
	v_mul_f32_e32 v38, 0x3fb8aa3b, v38
	v_exp_f32_e64 v38, v38 clamp
	v_add_f32_e32 v42, v42, v96
	v_add_f32_e32 v43, v43, v45
	v_add_f32_e32 v45, v124, v41
	v_add_f32_e32 v96, v125, v41
	v_cndmask_b32_e64 v41, 0, v38, s[90:91]
	v_pk_add_f32 v[38:39], v[106:107], v[36:37]
	v_add_f32_e32 v45, v113, v45
	v_add_f32_e32 v37, v127, v39
	v_add_f32_e32 v37, v112, v37
	v_mul_f32_e32 v37, 0x3fb8aa3b, v37
	v_exp_f32_e64 v37, v37 clamp
	v_add_f32_e32 v96, v111, v96
	v_cndmask_b32_e64 v105, 0, v37, s[92:93]
	v_add_f32_e32 v37, v128, v39
	v_add_f32_e32 v37, v47, v37
	v_mul_f32_e32 v37, 0x3fb8aa3b, v37
	v_exp_f32_e64 v37, v37 clamp
	s_nop 0
	v_cndmask_b32_e64 v47, 0, v37, s[94:95]
	v_add_f32_e32 v37, v46, v39
	v_add_f32_e32 v36, v36, v37
	v_mul_f32_e32 v36, 0x3fb8aa3b, v36
	v_exp_f32_e64 v36, v36 clamp
	v_mul_f32_e32 v44, 0x3fb8aa3b, v44
	v_mul_f32_e32 v40, 0x3fb8aa3b, v40
	v_cndmask_b32_e64 v46, 0, v36, s[96:97]
	v_add_f32_e32 v36, v102, v38
	v_add_f32_e32 v36, v36, v39
	v_mul_f32_e32 v36, 0x3fb8aa3b, v36
	v_exp_f32_e64 v36, v36 clamp
	v_mul_f32_e32 v42, 0x3fb8aa3b, v42
	v_mul_f32_e32 v43, 0x3fb8aa3b, v43
	v_mul_f32_e32 v45, 0x3fb8aa3b, v45
	v_cndmask_b32_e64 v106, 0, v36, s[4:5]
	v_add_f32_e32 v36, v102, v114
	v_add_f32_e32 v36, v121, v36
	v_add_f32_e32 v36, v119, v36
	v_mul_f32_e32 v36, 0x3fb8aa3b, v36
	v_exp_f32_e64 v36, v36 clamp
	v_mul_f32_e32 v96, 0x3fb8aa3b, v96
	v_exp_f32_e64 v44, v44 clamp
	v_exp_f32_e64 v40, v40 clamp
	v_cndmask_b32_e64 v48, 0, v36, s[6:7]
	v_add_f32_e32 v36, v102, v115
	v_add_f32_e32 v36, v121, v36
	v_add_f32_e32 v36, v118, v36
	v_mul_f32_e32 v36, 0x3fb8aa3b, v36
	v_exp_f32_e64 v36, v36 clamp
	v_exp_f32_e64 v42, v42 clamp
	v_exp_f32_e64 v43, v43 clamp
	v_exp_f32_e64 v45, v45 clamp
	v_cndmask_b32_e64 v49, 0, v36, s[8:9]
	v_add_f32_e32 v36, v102, v116
	v_add_f32_e32 v36, v121, v36
	v_add_f32_e32 v36, v117, v36
	v_mul_f32_e32 v36, 0x3fb8aa3b, v36
	v_exp_f32_e64 v36, v36 clamp
	v_fmac_f32_e32 v117, 0x3e000000, v51
	v_exp_f32_e64 v96, v96 clamp
	v_cndmask_b32_e64 v44, 0, v44, s[76:77]
	v_cndmask_b32_e64 v50, 0, v36, s[10:11]
	v_add_f32_e32 v36, v102, v117
	v_add_f32_e32 v36, v121, v36
	v_mul_f32_e32 v36, 0x3fb8aa3b, v36
	v_exp_f32_e64 v36, v36 clamp
	v_cndmask_b32_e64 v40, 0, v40, s[78:79]
	v_cndmask_b32_e64 v42, 0, v42, s[80:81]
	v_cndmask_b32_e64 v43, 0, v43, s[82:83]
	v_cndmask_b32_e64 v45, 0, v45, s[84:85]
	v_cndmask_b32_e64 v96, 0, v96, s[86:87]
	v_cndmask_b32_e32 v51, 0, v36, vcc
	v_cvt_pk_bf16_f32 v36, v44, v40
	v_cvt_pk_bf16_f32 v37, v42, v43
	v_cvt_pk_bf16_f32 v38, v45, v96
	v_cvt_pk_bf16_f32 v39, v104, v41
	v_add_f32_e32 v102, v102, v97
	s_mov_b32 s4, 0xc2d00000
	v_mfma_f32_32x32x16_bf16 v[4:19], v[80:83], v[36:39], v[4:19]
	v_cmp_gt_f32_e32 vcc, s4, v102
	s_cmp_eq_u64 vcc, exec
	s_cselect_b64 s[4:5], -1, 0
	v_cmp_eq_u32_e32 vcc, s28, v98
	s_or_b64 s[4:5], s[4:5], vcc
	s_add_i32 s28, s28, 1
	s_and_b64 s[4:5], exec, s[4:5]
	v_mfma_f32_32x32x16_bf16 v[20:35], v[76:79], v[36:39], v[20:35]
	v_cvt_pk_bf16_f32 v36, v105, v47
	v_cvt_pk_bf16_f32 v37, v46, v106
	v_cvt_pk_bf16_f32 v38, v48, v49
	v_cvt_pk_bf16_f32 v39, v50, v51
	s_or_b64 s[34:35], s[4:5], s[34:35]
	s_nop 0
	v_mfma_f32_32x32x16_bf16 v[4:19], v[72:75], v[36:39], v[4:19]
	v_mfma_f32_32x32x16_bf16 v[20:35], v[68:71], v[36:39], v[20:35]
	s_andn2_b64 exec, exec, s[34:35]
	s_cbranch_execz .Lsbu_exit
; __device__ __forceinline__ int crow(int r, int hi) { return (r & 3) + 8 * (r >> 2) + 4 * hi; }
; __device__ __forceinline__ void sb_load(SbFrags& F, const bf16_t* Pm, const bf16_t* VT, size_t tok0, int kv0, int h, int r32, int hi) {
;     const bf16_t* krow = Pm + (tok0 + kv0 + r32) * PW + PC_SBK + h * 64;
; #pragma unroll
;     for (int s = 0; s < 4; ++s) F.kf[s] = *(const bf16x8*)(krow + 16 * s + 8 * hi);
; #pragma unroll
;     for (int s = 0; s < 2; ++s) {
;         const bf16_t* v0p = VT + (size_t)(h * 64 + r32) * VTLD + tok0 + kv0 + 16 * s + 4 * hi; const bf16_t* v1p = v0p + (size_t)32 * VTLD;
;         F.v[4 * s + 0] = *(const s16x4*)v0p; F.v[4 * s + 1] = *(const s16x4*)(v0p + 8); F.v[4 * s + 2] = *(const s16x4*)v1p; F.v[4 * s + 3] = *(const s16x4*)(v1p + 8);
;     }
; }
; template <bool DRY> __device__ __forceinline__ void sb_unit(int b, int h, int qi, bf16_t* Pm, const bf16_t* VT) {
;     ...
;         sb_load(nxt, Pm, VT, tok0, (kt > 0 ? kt - 1 : 0) * 32, h, r32, hi);
;         f32x16 p = {};
; #pragma unroll
;         for (int s = 0; s < 4; ++s) p = __builtin_amdgcn_mfma_f32_32x32x16_bf16(cur.kf[s], qf[s], p, 0, 0, 0);
;         const bool diag = (kt == qi);
;         float lk[16], inner[16], Tg[4], TP[4], pre[4];
; #pragma unroll
;         for (int r = 0; r < 16; ++r) {
;             const float z = p[r] * 0.125f; p[r] = z;
;             const float e = __expf(-fabsf(z)); const float sp = fmaxf(z, 0.f) + __logf(1.f + e);
;             const bool valid = !diag || (crow(r, hi) < r32);
;             lk[r] = valid ? -sp : 0.f;
	v_med3_i32 v36, v100, 0, 1
	v_lshlrev_b32_e32 v36, 5, v36
	s_mov_b32 s4, 0x208000
	v_sub_u32_e32 v40, v99, v36
	v_add_co_u32_e32 v36, vcc, s4, v94
	v_mov_b32_e32 v41, v2
	s_nop 0
	v_addc_co_u32_e32 v37, vcc, 0, v95, vcc
	global_load_dwordx4 v[68:71], v[36:37], off offset:32
	global_load_dwordx4 v[72:75], v[94:95], off offset:32
	global_load_dwordx4 v[76:79], v[36:37], off
	global_load_dwordx4 v[80:83], v[94:95], off
	v_mad_u64_u32 v[36:37], s[4:5], v90, s24, v[92:93]
	v_mov_b32_e32 v38, v37
	v_mad_u64_u32 v[38:39], s[4:5], v91, s24, v[38:39]
	v_mov_b32_e32 v37, v38
	global_load_dwordx4 v[184:187], v[36:37], off offset:2400
	global_load_dwordx4 v[180:183], v[36:37], off offset:2368
	global_load_dwordx4 v[176:179], v[36:37], off offset:2336
	s_nop 0
	global_load_dwordx4 v[172:175], v[36:37], off offset:2304
	v_lshl_add_u64 v[90:91], v[0:1], 0, v[40:41]
	v_lshl_add_u64 v[94:95], v[40:41], 1, v[88:89]
	s_cmp_lg_u32 s28, 0
	s_cselect_b64 s[22:23], -1, 0
	s_or_b64 s[76:77], s[44:45], s[22:23]
	s_or_b64 s[78:79], s[46:47], s[22:23]
	s_or_b64 s[80:81], s[48:49], s[22:23]
	s_or_b64 s[88:89], s[56:57], s[22:23]
	s_or_b64 s[94:95], s[62:63], s[22:23]
	s_or_b64 s[96:97], s[64:65], s[22:23]
	s_or_b64 s[84:85], s[52:53], s[22:23]
	s_or_b64 s[86:87], s[54:55], s[22:23]
	s_or_b64 s[92:93], s[60:61], s[22:23]
	s_or_b64 s[90:91], s[58:59], s[22:23]
	s_or_b64 s[82:83], s[50:51], s[22:23]
	v_add_u32_e32 v100, -1, v100
	v_subrev_u32_e32 v99, 32, v99
	s_waitcnt vmcnt(8)
	v_mfma_f32_32x32x16_bf16 v[36:51], v[140:143], v[52:55], 0
	v_mfma_f32_32x32x16_bf16 v[36:51], v[144:147], v[56:59], v[36:51]
	v_mfma_f32_32x32x16_bf16 v[36:51], v[148:151], v[60:63], v[36:51]
	v_mfma_f32_32x32x16_bf16 v[36:51], v[152:155], v[64:67], v[36:51]
	v_permlane32_swap_b32_e32 v168, v170
	v_permlane32_swap_b32_e32 v169, v171
	v_permlane32_swap_b32_e32 v160, v162
	v_permlane32_swap_b32_e32 v161, v163
	v_permlane32_swap_b32_e32 v164, v166
	v_permlane32_swap_b32_e32 v165, v167
	v_permlane32_swap_b32_e32 v156, v158
	v_permlane32_swap_b32_e32 v157, v159
	s_nop 3
	v_mul_f32_e32 v96, 0x3e000000, v36
	v_mul_f32_e64 v97, |v96|, s25
	v_exp_f32_e32 v97, v97
	v_max_f32_e32 v96, 0, v96
	v_add_f32_e32 v97, 1.0, v97
	v_log_f32_e32 v97, v97
	s_nop 0
	v_fmamk_f32 v96, v97, 0x3f317217, v96
	v_cndmask_b32_e64 v103, 0, -v96, s[76:77]
	v_mul_f32_e32 v96, 0x3e000000, v37
	v_mul_f32_e64 v97, |v96|, s25
	v_exp_f32_e32 v97, v97
	v_max_f32_e32 v96, 0, v96
	v_fmamk_f32 v36, v36, 0x3e000000, v103
	v_add_f32_e32 v97, 1.0, v97
	v_log_f32_e32 v97, v97
	s_nop 0
	v_fmamk_f32 v96, v97, 0x3f317217, v96
	v_cndmask_b32_e64 v108, 0, -v96, s[78:79]
	v_mul_f32_e32 v96, 0x3e000000, v38
	v_mul_f32_e64 v97, |v96|, s25
	v_exp_f32_e32 v97, v97
	v_max_f32_e32 v96, 0, v96
	v_add_f32_e32 v97, 1.0, v97
	v_log_f32_e32 v97, v97
	s_nop 0
	v_fmamk_f32 v96, v97, 0x3f317217, v96
	v_cndmask_b32_e64 v109, 0, -v96, s[80:81]
	v_mul_f32_e32 v96, 0x3e000000, v39
	v_mul_f32_e64 v39, |v96|, s25
	v_exp_f32_e32 v39, v39
	v_max_f32_e32 v97, 0, v96
	v_add_f32_e32 v39, 1.0, v39
	v_log_f32_e32 v39, v39
	s_nop 0
	v_fmamk_f32 v110, v39, 0x3f317217, v97
	v_mul_f32_e32 v39, 0x3e000000, v40
	v_mul_f32_e64 v97, |v39|, s25
	v_exp_f32_e32 v97, v97
	v_max_f32_e32 v39, 0, v39
	v_add_f32_e32 v97, 1.0, v97
	v_log_f32_e32 v97, v97
	s_nop 0
	v_fmamk_f32 v39, v97, 0x3f317217, v39
	v_mul_f32_e32 v97, 0x3e000000, v41
	v_mul_f32_e64 v104, |v97|, s25
	v_exp_f32_e32 v104, v104
	v_max_f32_e32 v97, 0, v97
	v_cndmask_b32_e64 v39, 0, -v39, s[84:85]
	v_add_f32_e32 v104, 1.0, v104
	v_log_f32_e32 v104, v104
	s_nop 0
	v_fmamk_f32 v97, v104, 0x3f317217, v97
	v_mul_f32_e32 v104, 0x3e000000, v42
	v_mul_f32_e64 v105, |v104|, s25
	v_exp_f32_e32 v105, v105
	v_max_f32_e32 v104, 0, v104
	v_cndmask_b32_e64 v97, 0, -v97, s[86:87]
	v_add_f32_e32 v105, 1.0, v105
	v_log_f32_e32 v105, v105
	s_nop 0
	v_fmamk_f32 v104, v105, 0x3f317217, v104
	v_cndmask_b32_e64 v111, 0, -v104, s[88:89]
	v_mul_f32_e32 v104, 0x3e000000, v43
	v_mul_f32_e64 v43, |v104|, s25
	v_exp_f32_e32 v43, v43
	v_max_f32_e32 v105, 0, v104
	v_add_f32_e32 v43, 1.0, v43
	v_log_f32_e32 v43, v43
	s_nop 0
	v_fmamk_f32 v43, v43, 0x3f317217, v105
	v_mul_f32_e32 v105, 0x3e000000, v44
	v_mul_f32_e64 v106, |v105|, s25
	v_exp_f32_e32 v106, v106
	v_max_f32_e32 v105, 0, v105
	v_add_f32_e32 v106, 1.0, v106
	v_log_f32_e32 v106, v106
	s_nop 0
	v_fmamk_f32 v105, v106, 0x3f317217, v105
	v_mul_f32_e32 v106, 0x3e000000, v45
	v_mul_f32_e64 v107, |v106|, s25
	v_exp_f32_e32 v107, v107
	v_max_f32_e32 v106, 0, v106
	v_cndmask_b32_e64 v105, 0, -v105, s[92:93]
	v_add_f32_e32 v107, 1.0, v107
	v_log_f32_e32 v107, v107
	s_nop 0
	v_fmamk_f32 v106, v107, 0x3f317217, v106
	v_cndmask_b32_e64 v112, 0, -v106, s[94:95]
	v_mul_f32_e32 v106, 0x3e000000, v46
	v_mul_f32_e64 v107, |v106|, s25
	v_exp_f32_e32 v107, v107
	v_max_f32_e32 v106, 0, v106
	v_add_f32_e32 v107, 1.0, v107
	v_log_f32_e32 v107, v107
	s_nop 0
	v_fmamk_f32 v106, v107, 0x3f317217, v106
	v_cndmask_b32_e64 v113, 0, -v106, s[96:97]
	v_mul_f32_e32 v106, 0x3e000000, v47
	v_mul_f32_e64 v47, |v106|, s25
	v_exp_f32_e32 v47, v47
	v_max_f32_e32 v107, 0, v106
	v_add_f32_e32 v47, 1.0, v47
	v_log_f32_e32 v47, v47
	s_nop 0
	v_fmamk_f32 v47, v47, 0x3f317217, v107
	v_mul_f32_e32 v107, 0x3e000000, v48
	v_mul_f32_e64 v114, |v107|, s25
	v_exp_f32_e32 v114, v114
	v_max_f32_e32 v107, 0, v107
	s_or_b64 s[4:5], s[66:67], s[22:23]
	v_add_f32_e32 v114, 1.0, v114
	v_log_f32_e32 v114, v114
	s_nop 0
	v_fmamk_f32 v107, v114, 0x3f317217, v107
	s_or_b64 s[6:7], s[68:69], s[22:23]
	v_cndmask_b32_e64 v114, 0, -v107, s[6:7]
	v_mul_f32_e32 v107, 0x3e000000, v49
	v_mul_f32_e64 v115, |v107|, s25
	v_exp_f32_e32 v115, v115
	v_max_f32_e32 v107, 0, v107
	v_add_f32_e32 v115, 1.0, v115
	v_log_f32_e32 v115, v115
	s_nop 0
	v_fmamk_f32 v107, v115, 0x3f317217, v107
	s_or_b64 s[8:9], s[70:71], s[22:23]
	v_cndmask_b32_e64 v115, 0, -v107, s[8:9]
	v_mul_f32_e32 v107, 0x3e000000, v50
	v_mul_f32_e64 v116, |v107|, s25
	v_exp_f32_e32 v116, v116
	v_max_f32_e32 v107, 0, v107
	v_add_f32_e32 v116, 1.0, v116
	v_log_f32_e32 v116, v116
	s_nop 0
	v_fmamk_f32 v107, v116, 0x3f317217, v107
	s_or_b64 s[10:11], s[72:73], s[22:23]
	v_cndmask_b32_e64 v116, 0, -v107, s[10:11]
	v_mul_f32_e32 v107, 0x3e000000, v51
	v_mul_f32_e64 v117, |v107|, s25
	v_exp_f32_e32 v117, v117
	v_max_f32_e32 v107, 0, v107
	v_add_f32_e32 v117, 1.0, v117
	v_log_f32_e32 v117, v117
	s_nop 0
	v_fmamk_f32 v107, v117, 0x3f317217, v107
	s_or_b64 vcc, s[74:75], s[22:23]
	v_cndmask_b32_e64 v117, 0, -v107, vcc
	v_add_f32_e32 v118, v117, v116
	v_add_f32_e32 v119, v115, v118
	v_add_f32_e32 v107, v114, v119
	ds_bpermute_b32 v120, v101, v107
	v_fmac_f32_e32 v114, 0x3e000000, v48
	v_fmac_f32_e32 v115, 0x3e000000, v49
	v_fmac_f32_e32 v116, 0x3e000000, v50
	s_waitcnt lgkmcnt(0)
; __device__ __forceinline__ unsigned cvtpk(float lo, float hi) { f32x2_t v = {lo, hi}; bf16x2_t b = __builtin_convertvector(v, bf16x2_t); return __builtin_bit_cast(unsigned, b); }
; __device__ __forceinline__ int crow(int r, int hi) { return (r & 3) + 8 * (r >> 2) + 4 * hi; }
; template <bool DRY> __device__ __forceinline__ void sb_unit(int b, int h, int qi, bf16_t* Pm, const bf16_t* VT) {
;     ...
;         for (int r = 0; r < 16; ++r) {
;             const bool valid = !diag || (crow(r, hi) < r32);
;             const float ex = fminf(p[r] + lk[r] + R + pre[r >> 2] + inner[r], 0.f);
;             p[r] = valid ? __expf(ex) : 0.f;
;         }
;         R += run;
; #pragma unroll
;         for (int s = 0; s < 2; ++s) {
;             const u32x4 pw = (u32x4){cvtpk(p[8 * s + 0], p[8 * s + 1]), cvtpk(p[8 * s + 2], p[8 * s + 3]), cvtpk(p[8 * s + 4], p[8 * s + 5]), cvtpk(p[8 * s + 6], p[8 * s + 7])};
;             const bf16x8 pf = __builtin_bit_cast(bf16x8, pw);
;             const s16x4 l0 = cur.v[4 * s], h0 = cur.v[4 * s + 1], l1 = cur.v[4 * s + 2], h1 = cur.v[4 * s + 3];
;             const bf16x8 v0 = (bf16x8){l0[0], l0[1], l0[2], l0[3], h0[0], h0[1], h0[2], h0[3]};
;             const bf16x8 v1 = (bf16x8){l1[0], l1[1], l1[2], l1[3], h1[0], h1[1], h1[2], h1[3]};
;             o0 = __builtin_amdgcn_mfma_f32_32x32x16_bf16(v0, pf, o0, 0, 0, 0);
;             o1 = __builtin_amdgcn_mfma_f32_32x32x16_bf16(v1, pf, o1, 0, 0, 0);
;         }
;         if (__all(R < -104.f)) break;
;         cur = nxt;
;     }
; #pragma unroll
;     for (int g = 0; g < 4; ++g) {
;         u32x2 w0, w1;
;         w0.x = cvtpk(o0[4 * g], o0[4 * g + 1]); w0.y = cvtpk(o0[4 * g + 2], o0[4 * g + 3]);
;         w1.x = cvtpk(o1[4 * g], o1[4 * g + 1]); w1.y = cvtpk(o1[4 * g + 2], o1[4 * g + 3]);
;         if (!DRY || R == 1234.56789f) { *(u32x2*)(qrow + 8 * g + 4 * hi) = w0; *(u32x2*)(qrow + 32 + 8 * g + 4 * hi) = w1; }
;     }
; }
	v_add_f32_e32 v121, 0, v120
	v_add_f32_e32 v107, v107, v120
	v_add_f32_e32 v120, v102, v36
	v_fmamk_f32 v36, v37, 0x3e000000, v108
	v_add_f32_e32 v122, v102, v36
	v_fmamk_f32 v36, v38, 0x3e000000, v109
	v_add_f32_e32 v123, v102, v36
	v_fmamk_f32 v36, v40, 0x3e000000, v39
	v_add_f32_e32 v124, v102, v36
	v_fmamk_f32 v36, v41, 0x3e000000, v97
	v_add_f32_e32 v125, v102, v36
	v_fmamk_f32 v36, v42, 0x3e000000, v111
	v_add_f32_e32 v126, v102, v36
	v_fmamk_f32 v36, v44, 0x3e000000, v105
	v_add_f32_e32 v127, v102, v36
	v_fmamk_f32 v36, v45, 0x3e000000, v112
	v_add_f32_e32 v128, v102, v36
	v_fmamk_f32 v36, v46, 0x3e000000, v113
	v_add_f32_e32 v46, v102, v36
	v_cndmask_b32_e64 v36, 0, -v47, s[4:5]
	v_add_f32_e32 v47, v36, v113
	v_add_f32_e32 v112, v112, v47
	v_add_f32_e32 v38, v105, v112
	ds_bpermute_b32 v40, v101, v38
	v_add_f32_e32 v107, 0, v107
	v_cndmask_b32_e64 v121, 0, v121, s[12:13]
	s_waitcnt lgkmcnt(0)
	v_add_f32_e32 v38, v38, v40
	v_add_f32_e32 v105, v38, v107
	v_cndmask_b32_e64 v38, 0, -v43, s[90:91]
	v_add_f32_e32 v111, v38, v111
	v_add_f32_e32 v113, v97, v111
	v_cndmask_b32_e64 v37, 0, v40, s[12:13]
	v_add_f32_e32 v40, v39, v113
	ds_bpermute_b32 v41, v101, v40
	s_waitcnt lgkmcnt(0)
	v_cndmask_b32_e64 v39, 0, v41, s[12:13]
	v_add_f32_e32 v42, v40, v41
	v_pk_add_f32 v[40:41], v[104:105], v[38:39]
	v_add_f32_e32 v97, v42, v105
	v_cndmask_b32_e64 v42, 0, -v110, s[82:83]
	v_add_f32_e32 v39, v102, v40
	v_add_f32_e32 v40, v42, v109
	v_add_f32_e32 v104, v108, v40
	v_add_f32_e32 v44, v103, v104
	ds_bpermute_b32 v45, v101, v44
	s_waitcnt lgkmcnt(0)
	v_cndmask_b32_e64 v43, 0, v45, s[12:13]
	v_add_f32_e32 v103, v44, v45
	v_pk_add_f32 v[44:45], v[96:97], v[42:43]
	v_add_f32_e32 v97, v103, v97
	v_add_f32_e32 v43, v102, v44
	v_add_f32_e32 v44, v120, v45
	v_add_f32_e32 v44, v104, v44
	v_add_f32_e32 v104, v126, v41
	v_add_f32_e32 v38, v38, v104
	v_mul_f32_e32 v38, 0x3fb8aa3b, v38
	v_exp_f32_e64 v38, v38 clamp
	v_add_f32_e32 v96, v122, v45
	v_add_f32_e32 v40, v40, v96
	v_add_f32_e32 v96, v123, v45
	v_cndmask_b32_e64 v104, 0, v38, s[88:89]
	v_add_f32_e32 v38, v39, v41
	v_mul_f32_e32 v38, 0x3fb8aa3b, v38
	v_exp_f32_e64 v38, v38 clamp
	v_add_f32_e32 v42, v42, v96
	v_add_f32_e32 v43, v43, v45
	v_add_f32_e32 v45, v124, v41
	v_add_f32_e32 v96, v125, v41
	v_cndmask_b32_e64 v41, 0, v38, s[90:91]
	v_pk_add_f32 v[38:39], v[106:107], v[36:37]
	v_add_f32_e32 v45, v113, v45
	v_add_f32_e32 v37, v127, v39
	v_add_f32_e32 v37, v112, v37
	v_mul_f32_e32 v37, 0x3fb8aa3b, v37
	v_exp_f32_e64 v37, v37 clamp
	v_add_f32_e32 v96, v111, v96
	v_cndmask_b32_e64 v105, 0, v37, s[92:93]
	v_add_f32_e32 v37, v128, v39
	v_add_f32_e32 v37, v47, v37
	v_mul_f32_e32 v37, 0x3fb8aa3b, v37
	v_exp_f32_e64 v37, v37 clamp
	s_nop 0
	v_cndmask_b32_e64 v47, 0, v37, s[94:95]
	v_add_f32_e32 v37, v46, v39
	v_add_f32_e32 v36, v36, v37
	v_mul_f32_e32 v36, 0x3fb8aa3b, v36
	v_exp_f32_e64 v36, v36 clamp
	v_mul_f32_e32 v44, 0x3fb8aa3b, v44
	v_mul_f32_e32 v40, 0x3fb8aa3b, v40
	v_cndmask_b32_e64 v46, 0, v36, s[96:97]
	v_add_f32_e32 v36, v102, v38
	v_add_f32_e32 v36, v36, v39
	v_mul_f32_e32 v36, 0x3fb8aa3b, v36
	v_exp_f32_e64 v36, v36 clamp
	v_mul_f32_e32 v42, 0x3fb8aa3b, v42
	v_mul_f32_e32 v43, 0x3fb8aa3b, v43
	v_mul_f32_e32 v45, 0x3fb8aa3b, v45
	v_cndmask_b32_e64 v106, 0, v36, s[4:5]
	v_add_f32_e32 v36, v102, v114
	v_add_f32_e32 v36, v121, v36
	v_add_f32_e32 v36, v119, v36
	v_mul_f32_e32 v36, 0x3fb8aa3b, v36
	v_exp_f32_e64 v36, v36 clamp
	v_mul_f32_e32 v96, 0x3fb8aa3b, v96
	v_exp_f32_e64 v44, v44 clamp
	v_exp_f32_e64 v40, v40 clamp
	v_cndmask_b32_e64 v48, 0, v36, s[6:7]
	v_add_f32_e32 v36, v102, v115
	v_add_f32_e32 v36, v121, v36
	v_add_f32_e32 v36, v118, v36
	v_mul_f32_e32 v36, 0x3fb8aa3b, v36
	v_exp_f32_e64 v36, v36 clamp
	v_exp_f32_e64 v42, v42 clamp
	v_exp_f32_e64 v43, v43 clamp
	v_exp_f32_e64 v45, v45 clamp
	v_cndmask_b32_e64 v49, 0, v36, s[8:9]
	v_add_f32_e32 v36, v102, v116
	v_add_f32_e32 v36, v121, v36
	v_add_f32_e32 v36, v117, v36
	v_mul_f32_e32 v36, 0x3fb8aa3b, v36
	v_exp_f32_e64 v36, v36 clamp
	v_fmac_f32_e32 v117, 0x3e000000, v51
	v_exp_f32_e64 v96, v96 clamp
	v_cndmask_b32_e64 v44, 0, v44, s[76:77]
	v_cndmask_b32_e64 v50, 0, v36, s[10:11]
	v_add_f32_e32 v36, v102, v117
	v_add_f32_e32 v36, v121, v36
	v_mul_f32_e32 v36, 0x3fb8aa3b, v36
	v_exp_f32_e64 v36, v36 clamp
	v_cndmask_b32_e64 v40, 0, v40, s[78:79]
	v_cndmask_b32_e64 v42, 0, v42, s[80:81]
	v_cndmask_b32_e64 v43, 0, v43, s[82:83]
	v_cndmask_b32_e64 v45, 0, v45, s[84:85]
	v_cndmask_b32_e64 v96, 0, v96, s[86:87]
	v_cndmask_b32_e32 v51, 0, v36, vcc
	v_cvt_pk_bf16_f32 v36, v44, v40
	v_cvt_pk_bf16_f32 v37, v42, v43
	v_cvt_pk_bf16_f32 v38, v45, v96
	v_cvt_pk_bf16_f32 v39, v104, v41
	v_add_f32_e32 v102, v102, v97
	s_mov_b32 s4, 0xc2d00000
	v_mfma_f32_32x32x16_bf16 v[4:19], v[168:171], v[36:39], v[4:19]
	v_cmp_gt_f32_e32 vcc, s4, v102
	s_cmp_eq_u64 vcc, exec
	s_cselect_b64 s[4:5], -1, 0
	v_cmp_eq_u32_e32 vcc, s28, v98
	s_or_b64 s[4:5], s[4:5], vcc
	s_add_i32 s28, s28, 1
	s_and_b64 s[4:5], exec, s[4:5]
	v_mfma_f32_32x32x16_bf16 v[20:35], v[164:167], v[36:39], v[20:35]
	v_cvt_pk_bf16_f32 v36, v105, v47
	v_cvt_pk_bf16_f32 v37, v46, v106
	v_cvt_pk_bf16_f32 v38, v48, v49
	v_cvt_pk_bf16_f32 v39, v50, v51
	s_or_b64 s[34:35], s[4:5], s[34:35]
	s_nop 0
	v_mfma_f32_32x32x16_bf16 v[4:19], v[160:163], v[36:39], v[4:19]
	v_mfma_f32_32x32x16_bf16 v[20:35], v[156:159], v[36:39], v[20:35]
	s_andn2_b64 exec, exec, s[34:35]
	s_cbranch_execnz .LBB0_742
.Lsbu_exit:
	s_waitcnt vmcnt(0)
	s_or_b64 exec, exec, s[34:35]
	v_lshlrev_b32_e32 v0, 1, v86
	v_mov_b32_e32 v1, v2
	v_lshl_add_u64 v[0:1], v[84:85], 0, v[0:1]
	s_nop 4
	v_cvt_pk_bf16_f32 v4, v4, v5
	v_cvt_pk_bf16_f32 v5, v6, v7
	v_cvt_pk_bf16_f32 v6, v20, v21
	v_cvt_pk_bf16_f32 v7, v22, v23
	global_store_dwordx2 v[0:1], v[4:5], off offset:1280
	global_store_dwordx2 v[0:1], v[6:7], off offset:1344
	v_cvt_pk_bf16_f32 v4, v8, v9
	v_cvt_pk_bf16_f32 v5, v10, v11
	v_add_u32_e32 v3, s26, v3
	s_movk_i32 s4, 0x1fff
	v_cvt_pk_bf16_f32 v6, v24, v25
	v_cvt_pk_bf16_f32 v7, v26, v27
	global_store_dwordx2 v[0:1], v[4:5], off offset:1296
	global_store_dwordx2 v[0:1], v[6:7], off offset:1360
	v_cvt_pk_bf16_f32 v4, v12, v13
	v_cvt_pk_bf16_f32 v5, v14, v15
	v_cmp_lt_i32_e32 vcc, s4, v3
	v_cvt_pk_bf16_f32 v6, v28, v29
	v_cvt_pk_bf16_f32 v7, v30, v31
	global_store_dwordx2 v[0:1], v[4:5], off offset:1312
	global_store_dwordx2 v[0:1], v[6:7], off offset:1376
	v_cvt_pk_bf16_f32 v4, v16, v17
	v_cvt_pk_bf16_f32 v5, v18, v19
	s_or_b64 s[40:41], vcc, s[40:41]
	v_add_u16_e32 v87, s26, v87
	v_cvt_pk_bf16_f32 v6, v32, v33
	v_cvt_pk_bf16_f32 v7, v34, v35
	global_store_dwordx2 v[0:1], v[4:5], off offset:1328
	global_store_dwordx2 v[0:1], v[6:7], off offset:1392
	s_andn2_b64 exec, exec, s[40:41]
	s_cbranch_execnz .LBB0_741
